# banded per-tile row-max exchange via v_permlane32_swap instead of ds_bpermute (v60 + sw)
# speedup vs baseline: 1.0120x; 1.0045x over previous
.LBB0_908:
	s_nop 0
	v_max_f32_e32 v32, v1, v1
	v_max_f32_e32 v66, v0, v0
	v_max_f32_e32 v32, v66, v32
	v_max3_f32 v32, v32, v2, v3
	v_max3_f32 v32, v32, v4, v5
	v_max3_f32 v32, v32, v6, v7
	v_max3_f32 v32, v32, v8, v9
	v_max3_f32 v32, v32, v10, v11
	v_max3_f32 v32, v32, v12, v13
	v_max3_f32 v32, v32, v14, v15
	v_max3_f32 v32, v32, v16, v17
	v_max3_f32 v32, v32, v18, v19
	v_max3_f32 v32, v32, v20, v21
	v_max3_f32 v32, v32, v22, v23
	v_max3_f32 v32, v32, v24, v25
	v_max3_f32 v32, v32, v26, v27
	v_max3_f32 v32, v32, v28, v29
	v_max3_f32 v32, v32, v30, v31
	v_mov_b32_e32 v66, v32
	s_nop 1
	v_permlane32_swap_b32 v66, v32
	v_max_f32_e32 v66, v66, v66
	v_max_f32_e32 v32, v32, v66
	v_cmp_gt_f32_e32 vcc, v32, v213
	s_cbranch_vccz .LBB0_903
	v_max_f32_e32 v32, v32, v32
	v_max_f32_e32 v66, v213, v213
	v_max_f32_e32 v66, v66, v32
	v_sub_f32_e32 v32, v213, v66
	v_exp_f32_e32 v32, v32
	v_mov_b32_e32 v213, v66
	v_pk_mul_f32 v[64:65], v[64:65], v[32:33] op_sel_hi:[1,0]
	v_pk_mul_f32 v[62:63], v[62:63], v[32:33] op_sel_hi:[1,0]
	v_pk_mul_f32 v[60:61], v[60:61], v[32:33] op_sel_hi:[1,0]
	v_pk_mul_f32 v[58:59], v[58:59], v[32:33] op_sel_hi:[1,0]
	v_pk_mul_f32 v[56:57], v[56:57], v[32:33] op_sel_hi:[1,0]
	v_pk_mul_f32 v[54:55], v[54:55], v[32:33] op_sel_hi:[1,0]
	v_pk_mul_f32 v[52:53], v[52:53], v[32:33] op_sel_hi:[1,0]
	v_pk_mul_f32 v[50:51], v[50:51], v[32:33] op_sel_hi:[1,0]
	v_pk_mul_f32 v[48:49], v[48:49], v[32:33] op_sel_hi:[1,0]
	v_pk_mul_f32 v[46:47], v[46:47], v[32:33] op_sel_hi:[1,0]
	v_pk_mul_f32 v[44:45], v[44:45], v[32:33] op_sel_hi:[1,0]
	v_pk_mul_f32 v[42:43], v[42:43], v[32:33] op_sel_hi:[1,0]
	v_pk_mul_f32 v[40:41], v[40:41], v[32:33] op_sel_hi:[1,0]
	v_pk_mul_f32 v[38:39], v[38:39], v[32:33] op_sel_hi:[1,0]
	v_pk_mul_f32 v[36:37], v[36:37], v[32:33] op_sel_hi:[1,0]
	v_pk_mul_f32 v[34:35], v[34:35], v[32:33] op_sel_hi:[1,0]
	v_mul_f32_e32 v214, v214, v32
	s_branch .LBB0_903

.LBB0_923:
	s_nop 0
	v_max_f32_e32 v66, v1, v1
	v_max_f32_e32 v67, v0, v0
	v_max_f32_e32 v66, v67, v66
	v_max3_f32 v66, v66, v2, v3
	v_max3_f32 v66, v66, v4, v5
	v_max3_f32 v66, v66, v6, v7
	v_max3_f32 v66, v66, v8, v9
	v_max3_f32 v66, v66, v10, v11
	v_max3_f32 v66, v66, v12, v13
	v_max3_f32 v66, v66, v14, v15
	v_max3_f32 v66, v66, v16, v17
	v_max3_f32 v66, v66, v18, v19
	v_max3_f32 v66, v66, v20, v21
	v_max3_f32 v66, v66, v22, v23
	v_max3_f32 v66, v66, v24, v25
	v_max3_f32 v66, v66, v26, v27
	v_max3_f32 v66, v66, v28, v29
	v_max3_f32 v66, v66, v30, v31
	v_mov_b32_e32 v67, v66
	s_nop 1
	v_permlane32_swap_b32 v67, v66
	v_max_f32_e32 v67, v67, v67
	v_max_f32_e32 v66, v66, v67
	v_cmp_gt_f32_e32 vcc, v66, v210
	s_cbranch_vccz .LBB0_918
	v_max_f32_e32 v66, v66, v66
	v_max_f32_e32 v67, v210, v210
	v_max_f32_e32 v67, v67, v66
	v_sub_f32_e32 v66, v210, v67
	v_exp_f32_e32 v66, v66
	v_mov_b32_e32 v210, v67
	v_pk_mul_f32 v[64:65], v[64:65], v[66:67] op_sel_hi:[1,0]
	v_pk_mul_f32 v[62:63], v[62:63], v[66:67] op_sel_hi:[1,0]
	v_pk_mul_f32 v[60:61], v[60:61], v[66:67] op_sel_hi:[1,0]
	v_pk_mul_f32 v[58:59], v[58:59], v[66:67] op_sel_hi:[1,0]
	v_pk_mul_f32 v[56:57], v[56:57], v[66:67] op_sel_hi:[1,0]
	v_pk_mul_f32 v[54:55], v[54:55], v[66:67] op_sel_hi:[1,0]
	v_pk_mul_f32 v[52:53], v[52:53], v[66:67] op_sel_hi:[1,0]
	v_pk_mul_f32 v[50:51], v[50:51], v[66:67] op_sel_hi:[1,0]
	v_pk_mul_f32 v[48:49], v[48:49], v[66:67] op_sel_hi:[1,0]
	v_pk_mul_f32 v[46:47], v[46:47], v[66:67] op_sel_hi:[1,0]
	v_pk_mul_f32 v[44:45], v[44:45], v[66:67] op_sel_hi:[1,0]
	v_pk_mul_f32 v[42:43], v[42:43], v[66:67] op_sel_hi:[1,0]
	v_pk_mul_f32 v[40:41], v[40:41], v[66:67] op_sel_hi:[1,0]
	v_pk_mul_f32 v[38:39], v[38:39], v[66:67] op_sel_hi:[1,0]
	v_pk_mul_f32 v[36:37], v[36:37], v[66:67] op_sel_hi:[1,0]
	v_pk_mul_f32 v[34:35], v[34:35], v[66:67] op_sel_hi:[1,0]
	v_mul_f32_e32 v211, v211, v66
	s_branch .LBB0_918
